# loop-edge barrier rotation in differential-attention loops: per-tile barrier moved up to right after LDS staging stores, last 4 P.V MFMAs + pack tail after the release
# baseline (speedup 1.0000x reference)
.LBB0_465:
	s_add_i32 s57, s58, 1
	s_and_b32 s29, s55, 0x1fc000
	s_add_u32 s60, s48, s29
	s_addc_u32 s61, s49, 0
	s_and_b32 s29, s53, 0x1fc0
	s_mul_i32 s29, s29, 0x8c00
	global_load_dwordx4 v[162:165], v201, s[60:61]
	global_load_dwordx4 v[166:169], v208, s[60:61]
	s_add_u32 s60, s50, s29
	s_addc_u32 s61, s51, 0
	global_load_dwordx4 v[170:173], v209, s[60:61]
	global_load_dwordx4 v[174:177], v210, s[60:61]
	s_and_b32 s58, s58, 1
	s_mul_i32 s29, s58, 0x4400
	v_add_u32_e32 v186, s29, v195
	ds_read_b128 v[96:99], v186
	ds_read_b128 v[224:227], v186 offset:32
	ds_read_b128 v[228:231], v186 offset:8704
	ds_read_b128 v[232:235], v186 offset:8736
	s_xor_b32 s29, s58, 1
	s_mulk_i32 s29, 0x5000
	v_add_u32_e32 v187, s29, v202
	ds_read_b128 v[236:239], v186 offset:64
	ds_read_b64_tr_b16 v[240:241], v187 offset:34816
	ds_read_b64_tr_b16 v[242:243], v187 offset:37376
	v_dot2c_f32_bf16_e32 v222, 0x3f803f80, v158
	v_dot2c_f32_bf16_e32 v223, 0x3f803f80, v159
	s_waitcnt lgkmcnt(6)
	v_mfma_f32_32x32x16_bf16 v[112:127], v[96:99], v[130:133], v[80:95]
	s_waitcnt lgkmcnt(4)
	v_mfma_f32_32x32x16_bf16 v[96:111], v[228:231], v[130:133], v[80:95]
	ds_read_b128 v[228:231], v186 offset:8768
	ds_read_b64_tr_b16 v[244:245], v187 offset:34880
	ds_read_b64_tr_b16 v[246:247], v187 offset:37440
	v_dot2c_f32_bf16_e32 v221, 0x3f803f80, v160
	v_dot2c_f32_bf16_e32 v211, 0x3f803f80, v161
	v_mfma_f32_32x32x16_bf16 v[112:127], v[224:227], v[134:137], v[112:127]
	ds_read_b128 v[224:227], v186 offset:96
	ds_read_b64_tr_b16 v[248:249], v187 offset:34944
	ds_read_b64_tr_b16 v[250:251], v187 offset:37504
	v_dot2c_f32_bf16_e32 v222, 0x3f803f80, v154
	v_dot2c_f32_bf16_e32 v223, 0x3f803f80, v155
	s_waitcnt lgkmcnt(9)
	v_mfma_f32_32x32x16_bf16 v[96:111], v[232:235], v[134:137], v[96:111]
	ds_read_b128 v[232:235], v186 offset:8800
	ds_read_b64_tr_b16 v[214:215], v187 offset:35008
	ds_read_b64_tr_b16 v[216:217], v187 offset:37568
	v_dot2c_f32_bf16_e32 v221, 0x3f803f80, v156
	v_dot2c_f32_bf16_e32 v211, 0x3f803f80, v157
	v_dot2c_f32_bf16_e32 v222, 0x3f803f80, v150
	v_dot2c_f32_bf16_e32 v223, 0x3f803f80, v151
	s_waitcnt lgkmcnt(11)
	v_mfma_f32_32x32x16_bf16 v[112:127], v[236:239], v[138:141], v[112:127]
	v_dot2c_f32_bf16_e32 v221, 0x3f803f80, v152
	v_dot2c_f32_bf16_e32 v211, 0x3f803f80, v153
	s_waitcnt lgkmcnt(8)
	v_mfma_f32_32x32x16_bf16 v[96:111], v[228:231], v[138:141], v[96:111]
	v_dot2c_f32_bf16_e32 v222, 0x3f803f80, v146
	v_dot2c_f32_bf16_e32 v223, 0x3f803f80, v147
	s_waitcnt lgkmcnt(5)
	v_mfma_f32_32x32x16_bf16 v[112:127], v[224:227], v[142:145], v[112:127]
	v_dot2c_f32_bf16_e32 v221, 0x3f803f80, v148
	v_dot2c_f32_bf16_e32 v211, 0x3f803f80, v149
	s_waitcnt lgkmcnt(2)
	v_mfma_f32_32x32x16_bf16 v[96:111], v[232:235], v[142:145], v[96:111]
	v_mfma_f32_32x32x16_bf16 v[64:79], v[240:243], v[158:161], v[64:79]
	ds_read_b64_tr_b16 v[224:225], v187 offset:39936
	ds_read_b64_tr_b16 v[226:227], v187 offset:42496
	s_nop 4
	v_exp_f32_e32 v186, v112
	v_exp_f32_e32 v188, v113
	v_mfma_f32_32x32x16_bf16 v[48:63], v[244:247], v[158:161], v[48:63]
	ds_read_b64_tr_b16 v[228:229], v187 offset:40000
	ds_read_b64_tr_b16 v[230:231], v187 offset:42560
	v_exp_f32_e32 v189, v114
	v_exp_f32_e32 v212, v115
	v_mfma_f32_32x32x16_bf16 v[32:47], v[248:251], v[158:161], v[32:47]
	ds_read_b64_tr_b16 v[112:113], v187 offset:40064
	ds_read_b64_tr_b16 v[114:115], v187 offset:42624
	v_exp_f32_e32 v213, v116
	v_exp_f32_e32 v232, v117
	s_waitcnt lgkmcnt(6)
	v_mfma_f32_32x32x16_bf16 v[16:31], v[214:217], v[158:161], v[16:31]
	ds_read_b64_tr_b16 v[158:159], v187 offset:40128
	ds_read_b64_tr_b16 v[160:161], v187 offset:42688
	v_exp_f32_e32 v233, v118
	v_exp_f32_e32 v234, v119
	s_waitcnt lgkmcnt(6)
	v_mfma_f32_32x32x16_bf16 v[64:79], v[224:227], v[154:157], v[64:79]
	ds_read_b64_tr_b16 v[116:117], v187 offset:45056
	ds_read_b64_tr_b16 v[118:119], v187 offset:47616
	v_exp_f32_e32 v224, v120
	v_exp_f32_e32 v225, v121
	s_waitcnt lgkmcnt(6)
	v_mfma_f32_32x32x16_bf16 v[48:63], v[228:231], v[154:157], v[48:63]
	ds_read_b64_tr_b16 v[214:215], v187 offset:45120
	ds_read_b64_tr_b16 v[216:217], v187 offset:47680
	v_exp_f32_e32 v226, v122
	v_exp_f32_e32 v227, v123
	s_waitcnt lgkmcnt(6)
	v_mfma_f32_32x32x16_bf16 v[32:47], v[112:115], v[154:157], v[32:47]
	ds_read_b64_tr_b16 v[112:113], v187 offset:45184
	ds_read_b64_tr_b16 v[114:115], v187 offset:47744
	v_exp_f32_e32 v228, v124
	v_exp_f32_e32 v229, v125
	s_waitcnt lgkmcnt(6)
	v_mfma_f32_32x32x16_bf16 v[16:31], v[158:161], v[154:157], v[16:31]
	ds_read_b64_tr_b16 v[120:121], v187 offset:45248
	ds_read_b64_tr_b16 v[122:123], v187 offset:47808
	v_exp_f32_e32 v154, v126
	v_exp_f32_e32 v155, v127
	s_waitcnt lgkmcnt(6)
	v_mfma_f32_32x32x16_bf16 v[64:79], v[116:119], v[150:153], v[64:79]
	ds_read_b64_tr_b16 v[116:117], v187 offset:50176
	ds_read_b64_tr_b16 v[118:119], v187 offset:52736
	v_exp_f32_e32 v156, v96
	v_exp_f32_e32 v157, v97
	s_waitcnt lgkmcnt(6)
	v_mfma_f32_32x32x16_bf16 v[48:63], v[214:217], v[150:153], v[48:63]
	ds_read_b64_tr_b16 v[124:125], v187 offset:50240
	ds_read_b64_tr_b16 v[126:127], v187 offset:52800
	v_exp_f32_e32 v158, v98
	v_exp_f32_e32 v159, v99
	s_waitcnt lgkmcnt(6)
	v_mfma_f32_32x32x16_bf16 v[32:47], v[112:115], v[150:153], v[32:47]
	ds_read_b64_tr_b16 v[96:97], v187 offset:50304
	ds_read_b64_tr_b16 v[98:99], v187 offset:52864
	v_exp_f32_e32 v100, v100
	v_exp_f32_e32 v101, v101
	s_waitcnt lgkmcnt(6)
	v_mfma_f32_32x32x16_bf16 v[16:31], v[120:123], v[150:153], v[16:31]
	ds_read_b64_tr_b16 v[112:113], v187 offset:50368
	ds_read_b64_tr_b16 v[114:115], v187 offset:52928
	s_bitcmp1_b32 s57, 0
	s_cselect_b32 s29, 0x4400, 0
	s_add_i32 s29, s29, 0
	v_add_u32_e32 v187, s29, v182
	s_mulk_i32 s58, 0x5000
	s_waitcnt vmcnt(3)
	ds_write_b128 v187, v[162:165]
	v_add_u32_e32 v187, s29, v190
	s_add_i32 s29, s58, 0
	s_waitcnt vmcnt(2)
	ds_write_b128 v187, v[166:169]
	v_add_u32_e32 v187, s29, v196
	s_waitcnt vmcnt(1)
	ds_write_b128 v187, v[170:173] offset:34816
	v_add_u32_e32 v187, s29, v198
	s_waitcnt vmcnt(0)
	ds_write_b128 v187, v[174:177] offset:34816
	s_waitcnt lgkmcnt(0)
	s_barrier
	v_exp_f32_e32 v102, v102
	v_exp_f32_e32 v103, v103
	s_waitcnt lgkmcnt(10)
	v_mfma_f32_32x32x16_bf16 v[64:79], v[116:119], v[146:149], v[64:79]
	v_exp_f32_e32 v104, v104
	v_exp_f32_e32 v105, v105
	s_waitcnt lgkmcnt(8)
	v_mfma_f32_32x32x16_bf16 v[48:63], v[124:127], v[146:149], v[48:63]
	v_exp_f32_e32 v106, v106
	v_exp_f32_e32 v107, v107
	s_waitcnt lgkmcnt(6)
	v_mfma_f32_32x32x16_bf16 v[32:47], v[96:99], v[146:149], v[32:47]
	v_exp_f32_e32 v96, v108
	v_exp_f32_e32 v97, v109
	s_waitcnt lgkmcnt(4)
	v_mfma_f32_32x32x16_bf16 v[16:31], v[112:115], v[146:149], v[16:31]
	v_cvt_pk_bf16_f32 v148, v96, v97
	v_cvt_pk_bf16_f32 v147, v106, v107
	v_cvt_pk_bf16_f32 v146, v104, v105
	v_cvt_pk_bf16_f32 v153, v102, v103
	v_cvt_pk_bf16_f32 v152, v100, v101
	v_cvt_pk_bf16_f32 v151, v158, v159
	v_cvt_pk_bf16_f32 v150, v156, v157
	v_cvt_pk_bf16_f32 v157, v154, v155
	v_cvt_pk_bf16_f32 v156, v228, v229
	v_cvt_pk_bf16_f32 v155, v226, v227
	v_cvt_pk_bf16_f32 v154, v224, v225
	v_cvt_pk_bf16_f32 v161, v233, v234
	v_cvt_pk_bf16_f32 v160, v213, v232
	v_cvt_pk_bf16_f32 v159, v189, v212
	v_cvt_pk_bf16_f32 v158, v186, v188
	v_exp_f32_e32 v98, v110
	v_exp_f32_e32 v99, v111
	s_add_i32 s53, s53, 64
	s_addk_i32 s55, 0x4000
	v_cvt_pk_bf16_f32 v149, v98, v99
	s_cmp_eq_u32 s52, s57
	s_mov_b32 s58, s57
	s_cbranch_scc0 .LBB0_465
	s_mov_b32 s57, s54
	s_branch .LBB0_468

.LBB0_479:
	s_add_i32 s55, s54, 1
	s_and_b32 s29, s53, 0x1fc000
	s_cmpk_lg_i32 s54, 0x7f
	s_cselect_b32 s29, s29, 0x1fc000
	s_add_u32 s56, s48, s29
	s_addc_u32 s57, s49, 0
	global_load_dwordx4 v[170:173], v201, s[56:57]
	global_load_dwordx4 v[174:177], v208, s[56:57]
	s_add_u32 s56, s50, s52
	s_addc_u32 s57, s51, 0
	global_load_dwordx4 v[162:165], v209, s[56:57]
	global_load_dwordx4 v[166:169], v210, s[56:57]
	s_and_b32 s56, s54, 1
	s_mul_i32 s29, s56, 0x4400
	v_add_u32_e32 v186, s29, v195
	ds_read_b128 v[96:99], v186
	ds_read_b128 v[214:217], v186 offset:32
	ds_read_b128 v[224:227], v186 offset:8704
	ds_read_b128 v[228:231], v186 offset:8736
	s_xor_b32 s29, s56, 1
	s_mulk_i32 s29, 0x5000
	v_add_u32_e32 v187, s29, v202
	ds_read_b128 v[232:235], v186 offset:64
	ds_read_b64_tr_b16 v[236:237], v187 offset:34816
	ds_read_b64_tr_b16 v[238:239], v187 offset:37376
	v_dot2c_f32_bf16_e32 v222, 0x3f803f80, v158
	v_dot2c_f32_bf16_e32 v223, 0x3f803f80, v159
	s_waitcnt lgkmcnt(6)
	v_mfma_f32_32x32x16_bf16 v[112:127], v[96:99], v[130:133], v[80:95]
	s_waitcnt lgkmcnt(4)
	v_mfma_f32_32x32x16_bf16 v[96:111], v[224:227], v[130:133], v[80:95]
	ds_read_b128 v[224:227], v186 offset:8768
	ds_read_b64_tr_b16 v[240:241], v187 offset:34880
	ds_read_b64_tr_b16 v[242:243], v187 offset:37440
	v_dot2c_f32_bf16_e32 v221, 0x3f803f80, v160
	v_dot2c_f32_bf16_e32 v211, 0x3f803f80, v161
	v_mfma_f32_32x32x16_bf16 v[112:127], v[214:217], v[134:137], v[112:127]
	ds_read_b128 v[214:217], v186 offset:96
	ds_read_b64_tr_b16 v[244:245], v187 offset:34944
	ds_read_b64_tr_b16 v[246:247], v187 offset:37504
	v_dot2c_f32_bf16_e32 v222, 0x3f803f80, v154
	v_dot2c_f32_bf16_e32 v223, 0x3f803f80, v155
	s_waitcnt lgkmcnt(9)
	v_mfma_f32_32x32x16_bf16 v[96:111], v[228:231], v[134:137], v[96:111]
	ds_read_b128 v[228:231], v186 offset:8800
	ds_read_b64_tr_b16 v[248:249], v187 offset:35008
	ds_read_b64_tr_b16 v[250:251], v187 offset:37568
	v_dot2c_f32_bf16_e32 v221, 0x3f803f80, v156
	v_dot2c_f32_bf16_e32 v211, 0x3f803f80, v157
	v_dot2c_f32_bf16_e32 v222, 0x3f803f80, v150
	v_dot2c_f32_bf16_e32 v223, 0x3f803f80, v151
	s_waitcnt lgkmcnt(11)
	v_mfma_f32_32x32x16_bf16 v[112:127], v[232:235], v[138:141], v[112:127]
	v_dot2c_f32_bf16_e32 v221, 0x3f803f80, v152
	v_dot2c_f32_bf16_e32 v211, 0x3f803f80, v153
	s_waitcnt lgkmcnt(8)
	v_mfma_f32_32x32x16_bf16 v[96:111], v[224:227], v[138:141], v[96:111]
	v_dot2c_f32_bf16_e32 v222, 0x3f803f80, v146
	v_dot2c_f32_bf16_e32 v223, 0x3f803f80, v147
	s_waitcnt lgkmcnt(5)
	v_mfma_f32_32x32x16_bf16 v[112:127], v[214:217], v[142:145], v[112:127]
	v_dot2c_f32_bf16_e32 v221, 0x3f803f80, v148
	v_dot2c_f32_bf16_e32 v211, 0x3f803f80, v149
	s_waitcnt lgkmcnt(2)
	v_mfma_f32_32x32x16_bf16 v[96:111], v[228:231], v[142:145], v[96:111]
	v_mfma_f32_32x32x16_bf16 v[64:79], v[236:239], v[158:161], v[64:79]
	ds_read_b64_tr_b16 v[214:215], v187 offset:39936
	ds_read_b64_tr_b16 v[216:217], v187 offset:42496
	s_nop 4
	v_exp_f32_e32 v186, v112
	v_exp_f32_e32 v188, v113
	v_mfma_f32_32x32x16_bf16 v[48:63], v[240:243], v[158:161], v[48:63]
	ds_read_b64_tr_b16 v[224:225], v187 offset:40000
	ds_read_b64_tr_b16 v[226:227], v187 offset:42560
	v_exp_f32_e32 v189, v114
	v_exp_f32_e32 v212, v115
	v_mfma_f32_32x32x16_bf16 v[32:47], v[244:247], v[158:161], v[32:47]
	ds_read_b64_tr_b16 v[112:113], v187 offset:40064
	ds_read_b64_tr_b16 v[114:115], v187 offset:42624
	v_exp_f32_e32 v213, v116
	v_exp_f32_e32 v228, v117
	s_waitcnt lgkmcnt(6)
	v_mfma_f32_32x32x16_bf16 v[16:31], v[248:251], v[158:161], v[16:31]
	ds_read_b64_tr_b16 v[158:159], v187 offset:40128
	ds_read_b64_tr_b16 v[160:161], v187 offset:42688
	v_exp_f32_e32 v229, v118
	v_exp_f32_e32 v230, v119
	s_waitcnt lgkmcnt(6)
	v_mfma_f32_32x32x16_bf16 v[64:79], v[214:217], v[154:157], v[64:79]
	ds_read_b64_tr_b16 v[116:117], v187 offset:45056
	ds_read_b64_tr_b16 v[118:119], v187 offset:47616
	v_exp_f32_e32 v231, v120
	v_exp_f32_e32 v232, v121
	s_waitcnt lgkmcnt(6)
	v_mfma_f32_32x32x16_bf16 v[48:63], v[224:227], v[154:157], v[48:63]
	ds_read_b64_tr_b16 v[214:215], v187 offset:45120
	ds_read_b64_tr_b16 v[216:217], v187 offset:47680
	v_exp_f32_e32 v224, v122
	v_exp_f32_e32 v225, v123
	s_waitcnt lgkmcnt(6)
	v_mfma_f32_32x32x16_bf16 v[32:47], v[112:115], v[154:157], v[32:47]
	ds_read_b64_tr_b16 v[112:113], v187 offset:45184
	ds_read_b64_tr_b16 v[114:115], v187 offset:47744
	v_exp_f32_e32 v226, v124
	v_exp_f32_e32 v227, v125
	s_waitcnt lgkmcnt(6)
	v_mfma_f32_32x32x16_bf16 v[16:31], v[158:161], v[154:157], v[16:31]
	ds_read_b64_tr_b16 v[120:121], v187 offset:45248
	ds_read_b64_tr_b16 v[122:123], v187 offset:47808
	v_exp_f32_e32 v154, v126
	v_exp_f32_e32 v155, v127
	s_waitcnt lgkmcnt(6)
	v_mfma_f32_32x32x16_bf16 v[64:79], v[116:119], v[150:153], v[64:79]
	ds_read_b64_tr_b16 v[116:117], v187 offset:50176
	ds_read_b64_tr_b16 v[118:119], v187 offset:52736
	v_exp_f32_e32 v156, v96
	v_exp_f32_e32 v157, v97
	s_waitcnt lgkmcnt(6)
	v_mfma_f32_32x32x16_bf16 v[48:63], v[214:217], v[150:153], v[48:63]
	ds_read_b64_tr_b16 v[124:125], v187 offset:50240
	ds_read_b64_tr_b16 v[126:127], v187 offset:52800
	v_exp_f32_e32 v158, v98
	v_exp_f32_e32 v159, v99
	s_waitcnt lgkmcnt(6)
	v_mfma_f32_32x32x16_bf16 v[32:47], v[112:115], v[150:153], v[32:47]
	ds_read_b64_tr_b16 v[96:97], v187 offset:50304
	ds_read_b64_tr_b16 v[98:99], v187 offset:52864
	v_exp_f32_e32 v100, v100
	v_exp_f32_e32 v101, v101
	s_waitcnt lgkmcnt(6)
	v_mfma_f32_32x32x16_bf16 v[16:31], v[120:123], v[150:153], v[16:31]
	ds_read_b64_tr_b16 v[112:113], v187 offset:50368
	ds_read_b64_tr_b16 v[114:115], v187 offset:52928
	s_bitcmp1_b32 s55, 0
	s_cselect_b32 s29, 0x4400, 0
	s_add_i32 s29, s29, 0
	v_add_u32_e32 v187, s29, v182
	s_mulk_i32 s56, 0x5000
	s_waitcnt vmcnt(3)
	ds_write_b128 v187, v[170:173]
	v_add_u32_e32 v187, s29, v190
	s_add_i32 s29, s56, 0
	s_waitcnt vmcnt(2)
	ds_write_b128 v187, v[174:177]
	v_add_u32_e32 v187, s29, v196
	s_waitcnt vmcnt(1)
	ds_write_b128 v187, v[162:165] offset:34816
	v_add_u32_e32 v187, s29, v198
	s_waitcnt vmcnt(0)
	ds_write_b128 v187, v[166:169] offset:34816
	s_waitcnt lgkmcnt(0)
	s_barrier
	v_exp_f32_e32 v102, v102
	v_exp_f32_e32 v103, v103
	s_waitcnt lgkmcnt(10)
	v_mfma_f32_32x32x16_bf16 v[64:79], v[116:119], v[146:149], v[64:79]
	v_exp_f32_e32 v104, v104
	v_exp_f32_e32 v105, v105
	s_waitcnt lgkmcnt(8)
	v_mfma_f32_32x32x16_bf16 v[48:63], v[124:127], v[146:149], v[48:63]
	v_exp_f32_e32 v106, v106
	v_exp_f32_e32 v107, v107
	s_waitcnt lgkmcnt(6)
	v_mfma_f32_32x32x16_bf16 v[32:47], v[96:99], v[146:149], v[32:47]
	v_exp_f32_e32 v96, v108
	v_exp_f32_e32 v97, v109
	s_waitcnt lgkmcnt(4)
	v_mfma_f32_32x32x16_bf16 v[16:31], v[112:115], v[146:149], v[16:31]
	v_cvt_pk_bf16_f32 v148, v96, v97
	v_cvt_pk_bf16_f32 v147, v106, v107
	v_cvt_pk_bf16_f32 v146, v104, v105
	v_cvt_pk_bf16_f32 v153, v102, v103
	v_cvt_pk_bf16_f32 v152, v100, v101
	v_cvt_pk_bf16_f32 v151, v158, v159
	v_cvt_pk_bf16_f32 v150, v156, v157
	v_cvt_pk_bf16_f32 v157, v154, v155
	v_cvt_pk_bf16_f32 v156, v226, v227
	v_cvt_pk_bf16_f32 v155, v224, v225
	v_cvt_pk_bf16_f32 v154, v231, v232
	v_cvt_pk_bf16_f32 v161, v229, v230
	v_cvt_pk_bf16_f32 v160, v213, v228
	v_cvt_pk_bf16_f32 v159, v189, v212
	v_cvt_pk_bf16_f32 v158, v186, v188
	v_exp_f32_e32 v98, v110
	v_exp_f32_e32 v99, v111
	s_add_i32 s52, s52, 0x230000
	s_addk_i32 s53, 0x4000
	v_cvt_pk_bf16_f32 v149, v98, v99
	s_cmpk_lt_u32 s54, 0x7f
	s_mov_b32 s54, s55
	s_cbranch_scc1 .LBB0_479
